# DN/OUT prompt-tile epilogue also paired via v_permlane16_swap into 16-byte bf16 stores (on top of merged phases + wide GU epilogue)
# baseline (speedup 1.0000x reference)
; #define BAR() { __builtin_amdgcn_sched_barrier(0); __builtin_amdgcn_s_barrier(); asm volatile("" ::: "memory"); __builtin_amdgcn_sched_barrier(0); }
; DI void gemm_stream2(const bf16_t* __restrict__ A, int lda, const bf16_t* __restrict__ Bt, int ldb, int K, int m0, int n0, ...
;     ...
;     const int wave = __builtin_amdgcn_readfirstlane(tid >> 6), lane = tid & 63, wm = wave >> 1, wn = wave & 1, r = lane & 15, q = lane >> 4;
;     const int sc0 = ((lane & 7) ^ (lane >> 4)) * 8, sc1 = ((lane & 7) ^ (4 | (lane >> 4))) * 8;
;     const bf16_t* ga = A + (size_t)(m0 + wave * 32 + (lane >> 3)) * lda;
;     const bf16_t* gb = Bt + (size_t)(n0 + wave * 16 + (lane >> 3)) * ldb;
;     const bf16_t* gan = An + (size_t)(m0n + wave * 32 + (lane >> 3)) * ldan;
;     const bf16_t* gbn = Btn + (size_t)(n0n + wave * 16 + (lane >> 3)) * ldbn;
;     const unsigned wa = (unsigned)wave * 4096u, wbb = 32768u + (unsigned)wave * 2048u;
;     ...
;     const int sw = r >> 1;
;     const unsigned fo0 = (unsigned)(r * 128 + ((q ^ sw) << 4)), fo1 = (unsigned)(r * 128 + (((q ^ sw) ^ 4) << 4));
;     const unsigned aoff = (unsigned)(wm * 64) * 128u, boff = 32768u + (unsigned)(wn * 64) * 128u;
;     const int nk = K / 64;
;     const int grp = wave >> 2;
;     ...
;     int st = rg.st;
;     if (!rg.primed) {
;         const int s1p = st == 2 ? 0 : st + 1;
;         BAR();
;         STAGE(st, 0);
;         STAGE(s1p, 1);
;         asm volatile("s_waitcnt vmcnt(6)" ::: "memory");
;         BAR();
.Lgyd_lanes:
	v_and_b32_e32 v190, 63, v193
	v_and_b32_e32 v191, 15, v190
	v_lshrrev_b32_e32 v17, 4, v190
	v_lshrrev_b32_e32 v18, 3, v190
	v_and_b32_e32 v19, 7, v190
	v_xor_b32_e32 v195, v19, v17
	v_lshlrev_b32_e32 v195, 4, v195
	s_mov_b32 s1, 0x1600
	v_mad_u32_u24 v184, v18, s1, v195
	v_or_b32_e32 v195, 4, v17
	v_xor_b32_e32 v195, v19, v195
	v_lshlrev_b32_e32 v195, 4, v195
	v_add_u32_e32 v227, 8, v18
	v_mad_u32_u24 v185, v227, s1, v195
	v_lshrrev_b32_e32 v195, 1, v191
	v_xor_b32_e32 v195, v17, v195
	v_lshlrev_b32_e32 v195, 4, v195
	s_lshl_b32 s1, s33, 6
	v_add_u32_e32 v227, s1, v191
	v_lshl_add_u32 v186, v227, 7, v195
	v_xor_b32_e32 v187, 64, v186
	v_lshlrev_b32_e32 v228, 11, v227
	s_lshl_b32 s1, s36, 5
	v_add_u32_e32 v227, s1, v191
	v_lshl_add_u32 v188, v227, 7, v195
	v_add_u32_e32 v188, 0x10000, v188
	v_xor_b32_e32 v189, 64, v188
	s_lshl_b32 s1, s36, 6
	v_lshl_add_u32 v229, v17, 3, s1
	v_add_u32_e32 v237, v228, v229
	v_and_b32_e32 v227, 1, v17
	v_mul_u32_u24_e32 v227, 0x7ff8, v227
	v_add_u32_e32 v236, v237, v227
	s_add_i32 m0, s39, 0x10000
	s_nop 0
	global_load_lds_dwordx4 v184, s[70:71]
	s_add_i32 m0, s39, 0x10400
	s_nop 0
	global_load_lds_dwordx4 v185, s[70:71]
	s_add_u32 s70, s70, 0x80
	s_addc_u32 s71, s71, 0
	s_add_i32 m0, s39, 0x0
	s_nop 0
	global_load_lds_dwordx4 v184, s[66:67]
	s_add_i32 m0, s39, 0x400
	s_nop 0
	global_load_lds_dwordx4 v185, s[66:67]
	s_add_u32 s66, s66, 0x80
	s_addc_u32 s67, s67, 0
	s_add_i32 m0, s39, 0x14000
	s_nop 0
	global_load_lds_dwordx4 v184, s[72:73]
	s_add_i32 m0, s39, 0x14400
	s_nop 0
	global_load_lds_dwordx4 v185, s[72:73]
	s_add_u32 s72, s72, 0x80
	s_addc_u32 s73, s73, 0
	s_add_i32 m0, s39, 0x4000
	s_nop 0
	global_load_lds_dwordx4 v184, s[68:69]
	s_add_i32 m0, s39, 0x4400
	s_nop 0
	global_load_lds_dwordx4 v185, s[68:69]
	s_add_u32 s68, s68, 0x80
	s_addc_u32 s69, s69, 0
	s_add_i32 m0, s39, 0x18000
	s_nop 0
	global_load_lds_dwordx4 v184, s[70:71]
	s_add_i32 m0, s39, 0x18400
	s_nop 0
	global_load_lds_dwordx4 v185, s[70:71]
	s_add_u32 s70, s70, 0x80
	s_addc_u32 s71, s71, 0
	s_add_i32 m0, s39, 0x8000
	s_nop 0
	global_load_lds_dwordx4 v184, s[66:67]
	s_add_i32 m0, s39, 0x8400
	s_nop 0
	global_load_lds_dwordx4 v185, s[66:67]
	s_add_u32 s66, s66, 0x80
	s_addc_u32 s67, s67, 0
	s_add_i32 m0, s39, 0x1c000
	s_nop 0
	global_load_lds_dwordx4 v184, s[72:73]
	s_add_i32 m0, s39, 0x1c400
	s_nop 0
	global_load_lds_dwordx4 v185, s[72:73]
	s_add_u32 s72, s72, 0x80
	s_addc_u32 s73, s73, 0
	s_waitcnt vmcnt(8)
	s_barrier
	s_cmp_eq_u32 s33, 0
	s_cbranch_scc1 .Lgyd_lead
	s_barrier

; DI unsigned pk2(float lo, float hi) { const f32x2 v = {lo, hi}; return __builtin_bit_cast(unsigned, __builtin_convertvector(v, bf2_t)); }
;     ...
; #pragma unroll
;     for (int mi = 0; mi < 4; ++mi) {
;         const int row = m0 + wm * 64 + mi * 16 + r;
; #pragma unroll
;         for (int ni = 0; ni < 4; ++ni) {
;             const int col = n0 + wn * 64 + ni * 16 + q * 4;
;             if (MODE == 0) {
;                 u32x2 w; w.x = pk2(acc[mi][ni][0], acc[mi][ni][1]); w.y = pk2(acc[mi][ni][2], acc[mi][ni][3]);
;                 *(u32x2*)(Y + (size_t)row * DM + col) = w;
;             } else if (MODE == 1) {
;                 *(f32x4*)(YS + (size_t)(row - NP) * DM + col) = acc[mi][ni];
;             } else {
;                 *(f32x4*)(YS + (size_t)part * NS * DM + (size_t)(row - NP) * DM + col) = acc[mi][ni];
;             }
;         }
;     }
.Lgyd_epi:
	s_cmp_eq_u32 s55, 0
	s_cbranch_scc0 .Lgyd_epi_unit
	s_lshl_b32 s1, s57, 19
	s_lshl_b32 s62, s58, 9
	s_add_u32 s1, s1, s62
	s_add_u32 s1, s1, 0xac20000
	s_add_u32 s2, s88, s1
	s_addc_u32 s3, s89, 0
	s_nop 7
	s_nop 7
	v_cvt_pk_bf16_f32 v152, v24, v25
	v_cvt_pk_bf16_f32 v153, v26, v27
	v_cvt_pk_bf16_f32 v154, v32, v33
	v_cvt_pk_bf16_f32 v155, v34, v35
	s_nop 1
	v_permlane16_swap_b32_e32 v152, v154
	v_permlane16_swap_b32_e32 v153, v155
	global_store_dwordx4 v236, v[152:155], s[2:3] offset:0
	v_cvt_pk_bf16_f32 v156, v28, v29
	v_cvt_pk_bf16_f32 v157, v30, v31
	v_cvt_pk_bf16_f32 v158, v36, v37
	v_cvt_pk_bf16_f32 v159, v38, v39
	s_nop 1
	v_permlane16_swap_b32_e32 v156, v158
	v_permlane16_swap_b32_e32 v157, v159
	global_store_dwordx4 v236, v[156:159], s[2:3] offset:32
	v_cvt_pk_bf16_f32 v160, v56, v57
	v_cvt_pk_bf16_f32 v161, v58, v59
	v_cvt_pk_bf16_f32 v162, v64, v65
	v_cvt_pk_bf16_f32 v163, v66, v67
	s_nop 1
	v_permlane16_swap_b32_e32 v160, v162
	v_permlane16_swap_b32_e32 v161, v163
	global_store_dwordx4 v236, v[160:163], s[2:3] offset:256
	v_cvt_pk_bf16_f32 v164, v60, v61
	v_cvt_pk_bf16_f32 v165, v62, v63
	v_cvt_pk_bf16_f32 v166, v68, v69
	v_cvt_pk_bf16_f32 v167, v70, v71
	s_nop 1
	v_permlane16_swap_b32_e32 v164, v166
	v_permlane16_swap_b32_e32 v165, v167
	global_store_dwordx4 v236, v[164:167], s[2:3] offset:288
	s_add_u32 s2, s2, 0x10000
	s_addc_u32 s3, s3, 0
	v_cvt_pk_bf16_f32 v168, v40, v41
	v_cvt_pk_bf16_f32 v169, v42, v43
	v_cvt_pk_bf16_f32 v170, v48, v49
	v_cvt_pk_bf16_f32 v171, v50, v51
	s_nop 1
	v_permlane16_swap_b32_e32 v168, v170
	v_permlane16_swap_b32_e32 v169, v171
	global_store_dwordx4 v236, v[168:171], s[2:3] offset:0
	v_cvt_pk_bf16_f32 v172, v44, v45
	v_cvt_pk_bf16_f32 v173, v46, v47
	v_cvt_pk_bf16_f32 v174, v52, v53
	v_cvt_pk_bf16_f32 v175, v54, v55
	s_nop 1
	v_permlane16_swap_b32_e32 v172, v174
	v_permlane16_swap_b32_e32 v173, v175
	global_store_dwordx4 v236, v[172:175], s[2:3] offset:32
	v_cvt_pk_bf16_f32 v152, v72, v73
	v_cvt_pk_bf16_f32 v153, v74, v75
	v_cvt_pk_bf16_f32 v154, v80, v81
	v_cvt_pk_bf16_f32 v155, v82, v83
	s_nop 1
	v_permlane16_swap_b32_e32 v152, v154
	v_permlane16_swap_b32_e32 v153, v155
	global_store_dwordx4 v236, v[152:155], s[2:3] offset:256
	v_cvt_pk_bf16_f32 v156, v76, v77
	v_cvt_pk_bf16_f32 v157, v78, v79
	v_cvt_pk_bf16_f32 v158, v84, v85
	v_cvt_pk_bf16_f32 v159, v86, v87
	s_nop 1
	v_permlane16_swap_b32_e32 v156, v158
	v_permlane16_swap_b32_e32 v157, v159
	global_store_dwordx4 v236, v[156:159], s[2:3] offset:288
	s_add_u32 s2, s2, 0x30000
	s_addc_u32 s3, s3, 0
	v_cvt_pk_bf16_f32 v160, v88, v89
	v_cvt_pk_bf16_f32 v161, v90, v91
	v_cvt_pk_bf16_f32 v162, v96, v97
	v_cvt_pk_bf16_f32 v163, v98, v99
	s_nop 1
	v_permlane16_swap_b32_e32 v160, v162
	v_permlane16_swap_b32_e32 v161, v163
	global_store_dwordx4 v236, v[160:163], s[2:3] offset:0
	v_cvt_pk_bf16_f32 v164, v92, v93
	v_cvt_pk_bf16_f32 v165, v94, v95
	v_cvt_pk_bf16_f32 v166, v100, v101
	v_cvt_pk_bf16_f32 v167, v102, v103
	s_nop 1
	v_permlane16_swap_b32_e32 v164, v166
	v_permlane16_swap_b32_e32 v165, v167
	global_store_dwordx4 v236, v[164:167], s[2:3] offset:32
	v_cvt_pk_bf16_f32 v168, v120, v121
	v_cvt_pk_bf16_f32 v169, v122, v123
	v_cvt_pk_bf16_f32 v170, v128, v129
	v_cvt_pk_bf16_f32 v171, v130, v131
	s_nop 1
	v_permlane16_swap_b32_e32 v168, v170
	v_permlane16_swap_b32_e32 v169, v171
	global_store_dwordx4 v236, v[168:171], s[2:3] offset:256
	v_cvt_pk_bf16_f32 v172, v124, v125
	v_cvt_pk_bf16_f32 v173, v126, v127
	v_cvt_pk_bf16_f32 v174, v132, v133
	v_cvt_pk_bf16_f32 v175, v134, v135
	s_nop 1
	v_permlane16_swap_b32_e32 v172, v174
	v_permlane16_swap_b32_e32 v173, v175
	global_store_dwordx4 v236, v[172:175], s[2:3] offset:288
	s_add_u32 s2, s2, 0x10000
	s_addc_u32 s3, s3, 0
	v_cvt_pk_bf16_f32 v152, v104, v105
	v_cvt_pk_bf16_f32 v153, v106, v107
	v_cvt_pk_bf16_f32 v154, v112, v113
	v_cvt_pk_bf16_f32 v155, v114, v115
	s_nop 1
	v_permlane16_swap_b32_e32 v152, v154
	v_permlane16_swap_b32_e32 v153, v155
	global_store_dwordx4 v236, v[152:155], s[2:3] offset:0
	v_cvt_pk_bf16_f32 v156, v108, v109
	v_cvt_pk_bf16_f32 v157, v110, v111
	v_cvt_pk_bf16_f32 v158, v116, v117
	v_cvt_pk_bf16_f32 v159, v118, v119
	s_nop 1
	v_permlane16_swap_b32_e32 v156, v158
	v_permlane16_swap_b32_e32 v157, v159
	global_store_dwordx4 v236, v[156:159], s[2:3] offset:32
	v_cvt_pk_bf16_f32 v160, v136, v137
	v_cvt_pk_bf16_f32 v161, v138, v139
	v_cvt_pk_bf16_f32 v162, v144, v145
	v_cvt_pk_bf16_f32 v163, v146, v147
	s_nop 1
	v_permlane16_swap_b32_e32 v160, v162
	v_permlane16_swap_b32_e32 v161, v163
	global_store_dwordx4 v236, v[160:163], s[2:3] offset:256
	v_cvt_pk_bf16_f32 v164, v140, v141
	v_cvt_pk_bf16_f32 v165, v142, v143
	v_cvt_pk_bf16_f32 v166, v148, v149
	v_cvt_pk_bf16_f32 v167, v150, v151
	s_nop 1
	v_permlane16_swap_b32_e32 v164, v166
	v_permlane16_swap_b32_e32 v165, v167
	global_store_dwordx4 v236, v[164:167], s[2:3] offset:288
	s_branch .Lgyd_epi_done

; #define BAR() { __builtin_amdgcn_sched_barrier(0); __builtin_amdgcn_s_barrier(); asm volatile("" ::: "memory"); __builtin_amdgcn_sched_barrier(0); }
; DI void gemm_stream2(const bf16_t* __restrict__ A, int lda, const bf16_t* __restrict__ Bt, int ldb, int K, int m0, int n0, ...
;     ...
;     const int wave = __builtin_amdgcn_readfirstlane(tid >> 6), lane = tid & 63, wm = wave >> 1, wn = wave & 1, r = lane & 15, q = lane >> 4;
;     const int sc0 = ((lane & 7) ^ (lane >> 4)) * 8, sc1 = ((lane & 7) ^ (4 | (lane >> 4))) * 8;
;     const bf16_t* ga = A + (size_t)(m0 + wave * 32 + (lane >> 3)) * lda;
;     const bf16_t* gb = Bt + (size_t)(n0 + wave * 16 + (lane >> 3)) * ldb;
;     const bf16_t* gan = An + (size_t)(m0n + wave * 32 + (lane >> 3)) * ldan;
;     const bf16_t* gbn = Btn + (size_t)(n0n + wave * 16 + (lane >> 3)) * ldbn;
;     const unsigned wa = (unsigned)wave * 4096u, wbb = 32768u + (unsigned)wave * 2048u;
;     ...
;     const int sw = r >> 1;
;     const unsigned fo0 = (unsigned)(r * 128 + ((q ^ sw) << 4)), fo1 = (unsigned)(r * 128 + (((q ^ sw) ^ 4) << 4));
;     const unsigned aoff = (unsigned)(wm * 64) * 128u, boff = 32768u + (unsigned)(wn * 64) * 128u;
;     const int nk = K / 64;
;     const int grp = wave >> 2;
;     ...
;     int st = rg.st;
;     if (!rg.primed) {
;         const int s1p = st == 2 ? 0 : st + 1;
;         BAR();
;         STAGE(st, 0);
;         STAGE(s1p, 1);
;         asm volatile("s_waitcnt vmcnt(6)" ::: "memory");
;         BAR();
.Lgyo_lanes:
	v_and_b32_e32 v190, 63, v193
	v_and_b32_e32 v191, 15, v190
	v_lshrrev_b32_e32 v17, 4, v190
	v_lshrrev_b32_e32 v18, 3, v190
	v_and_b32_e32 v19, 7, v190
	v_xor_b32_e32 v195, v19, v17
	v_lshlrev_b32_e32 v195, 4, v195
	s_mov_b32 s1, 0x800
	v_mad_u32_u24 v184, v18, s1, v195
	v_or_b32_e32 v195, 4, v17
	v_xor_b32_e32 v195, v19, v195
	v_lshlrev_b32_e32 v195, 4, v195
	v_add_u32_e32 v227, 8, v18
	v_mad_u32_u24 v185, v227, s1, v195
	v_lshrrev_b32_e32 v195, 1, v191
	v_xor_b32_e32 v195, v17, v195
	v_lshlrev_b32_e32 v195, 4, v195
	s_lshl_b32 s1, s33, 6
	v_add_u32_e32 v227, s1, v191
	v_lshl_add_u32 v186, v227, 7, v195
	v_xor_b32_e32 v187, 64, v186
	v_lshlrev_b32_e32 v228, 11, v227
	s_lshl_b32 s1, s36, 5
	v_add_u32_e32 v227, s1, v191
	v_lshl_add_u32 v188, v227, 7, v195
	v_add_u32_e32 v188, 0x10000, v188
	v_xor_b32_e32 v189, 64, v188
	s_lshl_b32 s1, s36, 6
	v_lshl_add_u32 v229, v17, 3, s1
	v_add_u32_e32 v237, v228, v229
	v_and_b32_e32 v227, 1, v17
	v_mul_u32_u24_e32 v227, 0x7ff8, v227
	v_add_u32_e32 v236, v237, v227
	s_add_i32 m0, s39, 0x10000
	s_nop 0
	global_load_lds_dwordx4 v184, s[70:71]
	s_add_i32 m0, s39, 0x10400
	s_nop 0
	global_load_lds_dwordx4 v185, s[70:71]
	s_add_u32 s70, s70, 0x80
	s_addc_u32 s71, s71, 0
	s_add_i32 m0, s39, 0x0
	s_nop 0
	global_load_lds_dwordx4 v184, s[66:67]
	s_add_i32 m0, s39, 0x400
	s_nop 0
	global_load_lds_dwordx4 v185, s[66:67]
	s_add_u32 s66, s66, 0x80
	s_addc_u32 s67, s67, 0
	s_add_i32 m0, s39, 0x14000
	s_nop 0
	global_load_lds_dwordx4 v184, s[72:73]
	s_add_i32 m0, s39, 0x14400
	s_nop 0
	global_load_lds_dwordx4 v185, s[72:73]
	s_add_u32 s72, s72, 0x80
	s_addc_u32 s73, s73, 0
	s_add_i32 m0, s39, 0x4000
	s_nop 0
	global_load_lds_dwordx4 v184, s[68:69]
	s_add_i32 m0, s39, 0x4400
	s_nop 0
	global_load_lds_dwordx4 v185, s[68:69]
	s_add_u32 s68, s68, 0x80
	s_addc_u32 s69, s69, 0
	s_add_i32 m0, s39, 0x18000
	s_nop 0
	global_load_lds_dwordx4 v184, s[70:71]
	s_add_i32 m0, s39, 0x18400
	s_nop 0
	global_load_lds_dwordx4 v185, s[70:71]
	s_add_u32 s70, s70, 0x80
	s_addc_u32 s71, s71, 0
	s_add_i32 m0, s39, 0x8000
	s_nop 0
	global_load_lds_dwordx4 v184, s[66:67]
	s_add_i32 m0, s39, 0x8400
	s_nop 0
	global_load_lds_dwordx4 v185, s[66:67]
	s_add_u32 s66, s66, 0x80
	s_addc_u32 s67, s67, 0
	s_add_i32 m0, s39, 0x1c000
	s_nop 0
	global_load_lds_dwordx4 v184, s[72:73]
	s_add_i32 m0, s39, 0x1c400
	s_nop 0
	global_load_lds_dwordx4 v185, s[72:73]
	s_add_u32 s72, s72, 0x80
	s_addc_u32 s73, s73, 0
	s_waitcnt vmcnt(8)
	s_barrier
	s_cmp_eq_u32 s33, 0
	s_cbranch_scc1 .Lgyo_lead
	s_barrier
